# FF1 first-iteration peel plus the next unit's K-tile-1 upper A half requested before the epilogue stores: three of the peeled waits exclude the 16 stores (vmcnt(24))
# baseline (speedup 1.0000x reference)
.LBB0_854:
	v_mov_b32_e32 v123, 0
	s_andn2_b64 vcc, exec, s[46:47]
	v_mov_b32_e32 v122, v123
	v_mov_b32_e32 v121, v123
	v_mov_b32_e32 v120, v123
	v_mov_b32_e32 v127, v123
	v_mov_b32_e32 v126, v123
	v_mov_b32_e32 v125, v123
	v_mov_b32_e32 v124, v123
	v_mov_b32_e32 v111, v123
	v_mov_b32_e32 v110, v123
	v_mov_b32_e32 v109, v123
	v_mov_b32_e32 v108, v123
	v_mov_b32_e32 v107, v123
	v_mov_b32_e32 v106, v123
	v_mov_b32_e32 v105, v123
	v_mov_b32_e32 v104, v123
	v_mov_b32_e32 v95, v123
	v_mov_b32_e32 v94, v123
	v_mov_b32_e32 v93, v123
	v_mov_b32_e32 v92, v123
	v_mov_b32_e32 v91, v123
	v_mov_b32_e32 v90, v123
	v_mov_b32_e32 v89, v123
	v_mov_b32_e32 v88, v123
	v_mov_b32_e32 v79, v123
	v_mov_b32_e32 v78, v123
	v_mov_b32_e32 v77, v123
	v_mov_b32_e32 v76, v123
	v_mov_b32_e32 v75, v123
	v_mov_b32_e32 v74, v123
	v_mov_b32_e32 v73, v123
	v_mov_b32_e32 v72, v123
	v_mov_b32_e32 v119, v123
	v_mov_b32_e32 v118, v123
	v_mov_b32_e32 v117, v123
	v_mov_b32_e32 v116, v123
	v_mov_b32_e32 v115, v123
	v_mov_b32_e32 v114, v123
	v_mov_b32_e32 v113, v123
	v_mov_b32_e32 v112, v123
	v_mov_b32_e32 v103, v123
	v_mov_b32_e32 v102, v123
	v_mov_b32_e32 v101, v123
	v_mov_b32_e32 v100, v123
	v_mov_b32_e32 v99, v123
	v_mov_b32_e32 v98, v123
	v_mov_b32_e32 v97, v123
	v_mov_b32_e32 v96, v123
	v_mov_b32_e32 v87, v123
	v_mov_b32_e32 v86, v123
	v_mov_b32_e32 v85, v123
	v_mov_b32_e32 v84, v123
	v_mov_b32_e32 v83, v123
	v_mov_b32_e32 v82, v123
	v_mov_b32_e32 v81, v123
	v_mov_b32_e32 v80, v123
	v_mov_b32_e32 v71, v123
	v_mov_b32_e32 v70, v123
	v_mov_b32_e32 v69, v123
	v_mov_b32_e32 v68, v123
	v_mov_b32_e32 v67, v123
	v_mov_b32_e32 v66, v123
	v_mov_b32_e32 v65, v123
	v_mov_b32_e32 v64, v123
	v_mov_b32_e32 v63, v123
	v_mov_b32_e32 v62, v123
	v_mov_b32_e32 v61, v123
	v_mov_b32_e32 v60, v123
	v_mov_b32_e32 v59, v123
	v_mov_b32_e32 v58, v123
	v_mov_b32_e32 v57, v123
	v_mov_b32_e32 v56, v123
	v_mov_b32_e32 v47, v123
	v_mov_b32_e32 v46, v123
	v_mov_b32_e32 v45, v123
	v_mov_b32_e32 v44, v123
	v_mov_b32_e32 v43, v123
	v_mov_b32_e32 v42, v123
	v_mov_b32_e32 v41, v123
	v_mov_b32_e32 v40, v123
	v_mov_b32_e32 v31, v123
	v_mov_b32_e32 v30, v123
	v_mov_b32_e32 v29, v123
	v_mov_b32_e32 v28, v123
	v_mov_b32_e32 v27, v123
	v_mov_b32_e32 v26, v123
	v_mov_b32_e32 v25, v123
	v_mov_b32_e32 v24, v123
	v_mov_b32_e32 v15, v123
	v_mov_b32_e32 v14, v123
	v_mov_b32_e32 v13, v123
	v_mov_b32_e32 v12, v123
	v_mov_b32_e32 v11, v123
	v_mov_b32_e32 v10, v123
	v_mov_b32_e32 v9, v123
	v_mov_b32_e32 v8, v123
	v_mov_b32_e32 v55, v123
	v_mov_b32_e32 v54, v123
	v_mov_b32_e32 v53, v123
	v_mov_b32_e32 v52, v123
	v_mov_b32_e32 v51, v123
	v_mov_b32_e32 v50, v123
	v_mov_b32_e32 v49, v123
	v_mov_b32_e32 v48, v123
	v_mov_b32_e32 v39, v123
	v_mov_b32_e32 v38, v123
	v_mov_b32_e32 v37, v123
	v_mov_b32_e32 v36, v123
	v_mov_b32_e32 v35, v123
	v_mov_b32_e32 v34, v123
	v_mov_b32_e32 v33, v123
	v_mov_b32_e32 v32, v123
	v_mov_b32_e32 v23, v123
	v_mov_b32_e32 v22, v123
	v_mov_b32_e32 v21, v123
	v_mov_b32_e32 v20, v123
	v_mov_b32_e32 v19, v123
	v_mov_b32_e32 v18, v123
	v_mov_b32_e32 v17, v123
	v_mov_b32_e32 v16, v123
	v_mov_b32_e32 v7, v123
	v_mov_b32_e32 v6, v123
	v_mov_b32_e32 v5, v123
	v_mov_b32_e32 v4, v123
	v_mov_b32_e32 v3, v123
	v_mov_b32_e32 v2, v123
	v_mov_b32_e32 v1, v123
	v_mov_b32_e32 v0, v123
	s_cbranch_vccnz .LBB0_857
	s_add_u32 s60, s60, 0x80
	s_addc_u32 s61, s61, 0
	s_add_u32 s82, s62, 0x100
	v_mov_b32_e32 v0, 0
	s_addc_u32 s83, s63, 0
	s_mov_b32 s62, 0
	v_mov_b32_e32 v1, v0
	v_mov_b32_e32 v2, v0
	v_mov_b32_e32 v3, v0
	v_mov_b32_e32 v4, v0
	v_mov_b32_e32 v5, v0
	v_mov_b32_e32 v6, v0
	v_mov_b32_e32 v7, v0
	v_mov_b32_e32 v16, v0
	v_mov_b32_e32 v17, v0
	v_mov_b32_e32 v18, v0
	v_mov_b32_e32 v19, v0
	v_mov_b32_e32 v20, v0
	v_mov_b32_e32 v21, v0
	v_mov_b32_e32 v22, v0
	v_mov_b32_e32 v23, v0
	v_mov_b32_e32 v32, v0
	v_mov_b32_e32 v33, v0
	v_mov_b32_e32 v34, v0
	v_mov_b32_e32 v35, v0
	v_mov_b32_e32 v36, v0
	v_mov_b32_e32 v37, v0
	v_mov_b32_e32 v38, v0
	v_mov_b32_e32 v39, v0
	v_mov_b32_e32 v48, v0
	v_mov_b32_e32 v49, v0
	v_mov_b32_e32 v50, v0
	v_mov_b32_e32 v51, v0
	v_mov_b32_e32 v52, v0
	v_mov_b32_e32 v53, v0
	v_mov_b32_e32 v54, v0
	v_mov_b32_e32 v55, v0
	v_mov_b32_e32 v8, v0
	v_mov_b32_e32 v9, v0
	v_mov_b32_e32 v10, v0
	v_mov_b32_e32 v11, v0
	v_mov_b32_e32 v12, v0
	v_mov_b32_e32 v13, v0
	v_mov_b32_e32 v14, v0
	v_mov_b32_e32 v15, v0
	v_mov_b32_e32 v24, v0
	v_mov_b32_e32 v25, v0
	v_mov_b32_e32 v26, v0
	v_mov_b32_e32 v27, v0
	v_mov_b32_e32 v28, v0
	v_mov_b32_e32 v29, v0
	v_mov_b32_e32 v30, v0
	v_mov_b32_e32 v31, v0
	v_mov_b32_e32 v40, v0
	v_mov_b32_e32 v41, v0
	v_mov_b32_e32 v42, v0
	v_mov_b32_e32 v43, v0
	v_mov_b32_e32 v44, v0
	v_mov_b32_e32 v45, v0
	v_mov_b32_e32 v46, v0
	v_mov_b32_e32 v47, v0
	v_mov_b32_e32 v56, v0
	v_mov_b32_e32 v57, v0
	v_mov_b32_e32 v58, v0
	v_mov_b32_e32 v59, v0
	v_mov_b32_e32 v60, v0
	v_mov_b32_e32 v61, v0
	v_mov_b32_e32 v62, v0
	v_mov_b32_e32 v63, v0
	v_mov_b32_e32 v64, v0
	v_mov_b32_e32 v65, v0
	v_mov_b32_e32 v66, v0
	v_mov_b32_e32 v67, v0
	v_mov_b32_e32 v68, v0
	v_mov_b32_e32 v69, v0
	v_mov_b32_e32 v70, v0
	v_mov_b32_e32 v71, v0
	v_mov_b32_e32 v80, v0
	v_mov_b32_e32 v81, v0
	v_mov_b32_e32 v82, v0
	v_mov_b32_e32 v83, v0
	v_mov_b32_e32 v84, v0
	v_mov_b32_e32 v85, v0
	v_mov_b32_e32 v86, v0
	v_mov_b32_e32 v87, v0
	v_mov_b32_e32 v96, v0
	v_mov_b32_e32 v97, v0
	v_mov_b32_e32 v98, v0
	v_mov_b32_e32 v99, v0
	v_mov_b32_e32 v100, v0
	v_mov_b32_e32 v101, v0
	v_mov_b32_e32 v102, v0
	v_mov_b32_e32 v103, v0
	v_mov_b32_e32 v112, v0
	v_mov_b32_e32 v113, v0
	v_mov_b32_e32 v114, v0
	v_mov_b32_e32 v115, v0
	v_mov_b32_e32 v116, v0
	v_mov_b32_e32 v117, v0
	v_mov_b32_e32 v118, v0
	v_mov_b32_e32 v119, v0
	v_mov_b32_e32 v72, v0
	v_mov_b32_e32 v73, v0
	v_mov_b32_e32 v74, v0
	v_mov_b32_e32 v75, v0
	v_mov_b32_e32 v76, v0
	v_mov_b32_e32 v77, v0
	v_mov_b32_e32 v78, v0
	v_mov_b32_e32 v79, v0
	v_mov_b32_e32 v88, v0
	v_mov_b32_e32 v89, v0
	v_mov_b32_e32 v90, v0
	v_mov_b32_e32 v91, v0
	v_mov_b32_e32 v92, v0
	v_mov_b32_e32 v93, v0
	v_mov_b32_e32 v94, v0
	v_mov_b32_e32 v95, v0
	v_mov_b32_e32 v104, v0
	v_mov_b32_e32 v105, v0
	v_mov_b32_e32 v106, v0
	v_mov_b32_e32 v107, v0
	v_mov_b32_e32 v108, v0
	v_mov_b32_e32 v109, v0
	v_mov_b32_e32 v110, v0
	v_mov_b32_e32 v111, v0
	v_mov_b32_e32 v124, v0
	v_mov_b32_e32 v125, v0
	v_mov_b32_e32 v126, v0
	v_mov_b32_e32 v127, v0
	v_mov_b32_e32 v120, v0
	v_mov_b32_e32 v121, v0
	v_mov_b32_e32 v122, v0
	v_mov_b32_e32 v123, v0
	s_cmp_eq_u32 s29, 1
	s_cbranch_scc1 .LBB0_856
	ds_read_b128 v[152:155], v149
	ds_read_b128 v[156:159], v149 offset:1024
	ds_read_b128 v[160:163], v149 offset:2048
	ds_read_b128 v[164:167], v149 offset:3072
	ds_read_b128 v[168:171], v150
	ds_read_b128 v[172:175], v150 offset:1024
	ds_read_b128 v[176:179], v150 offset:2048
	ds_read_b128 v[180:183], v150 offset:3072
	s_add_i32 s84, s62, 2
	s_add_u32 s85, s60, 0x80
	s_addc_u32 s63, s61, 0
	s_cmp_eq_u32 s65, s62
	s_cselect_b32 s62, s10, s85
	s_cselect_b32 s63, s11, s63
	s_cselect_b32 s87, s59, s83
	s_cselect_b32 s86, s58, s82
	v_lshl_add_u64 v[144:145], s[60:61], 0, v[136:137]
	s_add_i32 m0, s25, 0xc000
	ds_read_b128 v[184:187], v151
	ds_read_b128 v[188:191], v151 offset:1024
	ds_read_b128 v[192:195], v151 offset:2048
	ds_read_b128 v[196:199], v151 offset:3072
	ds_read_b128 v[200:203], v151 offset:4096
	ds_read_b128 v[204:207], v151 offset:5120
	ds_read_b128 v[208:211], v151 offset:6144
	ds_read_b128 v[212:215], v151 offset:7168
	v_lshl_add_u64 v[144:145], s[60:61], 0, v[138:139]
	s_add_i32 m0, s25, 0xe000
	s_nop 0
	s_waitcnt vmcnt(24)
	s_waitcnt lgkmcnt(0)
	s_barrier
	s_setprio 1
	s_waitcnt lgkmcnt(0)
	v_mfma_f32_16x16x32_bf16 v[120:123], v[152:155], v[184:187], v[120:123]
	v_mfma_f32_16x16x32_bf16 v[124:127], v[160:163], v[184:187], v[124:127]
	v_mfma_f32_16x16x32_bf16 v[108:111], v[152:155], v[192:195], v[108:111]
	v_mfma_f32_16x16x32_bf16 v[104:107], v[160:163], v[192:195], v[104:107]
	v_mfma_f32_16x16x32_bf16 v[92:95], v[152:155], v[200:203], v[92:95]
	v_mfma_f32_16x16x32_bf16 v[88:91], v[160:163], v[200:203], v[88:91]
	v_mfma_f32_16x16x32_bf16 v[76:79], v[152:155], v[208:211], v[76:79]
	v_mfma_f32_16x16x32_bf16 v[72:75], v[160:163], v[208:211], v[72:75]
	v_mfma_f32_16x16x32_bf16 v[120:123], v[156:159], v[188:191], v[120:123]
	v_mfma_f32_16x16x32_bf16 v[124:127], v[164:167], v[188:191], v[124:127]
	v_mfma_f32_16x16x32_bf16 v[108:111], v[156:159], v[196:199], v[108:111]
	v_mfma_f32_16x16x32_bf16 v[104:107], v[164:167], v[196:199], v[104:107]
	v_mfma_f32_16x16x32_bf16 v[92:95], v[156:159], v[204:207], v[92:95]
	v_mfma_f32_16x16x32_bf16 v[88:91], v[164:167], v[204:207], v[88:91]
	v_mfma_f32_16x16x32_bf16 v[76:79], v[156:159], v[212:215], v[76:79]
	v_mfma_f32_16x16x32_bf16 v[72:75], v[164:167], v[212:215], v[72:75]
	s_setprio 0
	s_setprio 1
	v_mfma_f32_16x16x32_bf16 v[116:119], v[168:171], v[184:187], v[116:119]
	v_mfma_f32_16x16x32_bf16 v[112:115], v[176:179], v[184:187], v[112:115]
	v_mfma_f32_16x16x32_bf16 v[100:103], v[168:171], v[192:195], v[100:103]
	v_mfma_f32_16x16x32_bf16 v[96:99], v[176:179], v[192:195], v[96:99]
	v_mfma_f32_16x16x32_bf16 v[84:87], v[168:171], v[200:203], v[84:87]
	v_mfma_f32_16x16x32_bf16 v[80:83], v[176:179], v[200:203], v[80:83]
	v_mfma_f32_16x16x32_bf16 v[68:71], v[168:171], v[208:211], v[68:71]
	v_mfma_f32_16x16x32_bf16 v[64:67], v[176:179], v[208:211], v[64:67]
	v_mfma_f32_16x16x32_bf16 v[116:119], v[172:175], v[188:191], v[116:119]
	v_mfma_f32_16x16x32_bf16 v[112:115], v[180:183], v[188:191], v[112:115]
	v_mfma_f32_16x16x32_bf16 v[100:103], v[172:175], v[196:199], v[100:103]
	v_mfma_f32_16x16x32_bf16 v[96:99], v[180:183], v[196:199], v[96:99]
	v_mfma_f32_16x16x32_bf16 v[84:87], v[172:175], v[204:207], v[84:87]
	v_mfma_f32_16x16x32_bf16 v[80:83], v[180:183], v[204:207], v[80:83]
	v_mfma_f32_16x16x32_bf16 v[68:71], v[172:175], v[212:215], v[68:71]
	v_mfma_f32_16x16x32_bf16 v[64:67], v[180:183], v[212:215], v[64:67]
	s_setprio 0
	s_barrier
	s_add_i32 s85, s67, s24
	v_lshl_add_u64 v[144:145], s[86:87], 0, v[132:133]
	s_mov_b32 m0, s85
	ds_read_b128 v[184:187], v151 offset:16384
	ds_read_b128 v[188:191], v151 offset:17408
	ds_read_b128 v[192:195], v151 offset:18432
	ds_read_b128 v[196:199], v151 offset:19456
	ds_read_b128 v[200:203], v151 offset:20480
	ds_read_b128 v[204:207], v151 offset:21504
	ds_read_b128 v[208:211], v151 offset:22528
	ds_read_b128 v[212:215], v151 offset:23552
	global_load_lds_dwordx4 v[144:145], off
	s_add_i32 m0, s85, 0x2000
	v_lshl_add_u64 v[216:217], s[86:87], 0, v[128:129]
	s_add_u32 s86, s86, s34
	s_addc_u32 s87, s87, s35
	s_add_i32 s85, s68, s24
	global_load_lds_dwordx4 v[216:217], off
	v_lshl_add_u64 v[218:219], s[86:87], 0, v[132:133]
	s_mov_b32 m0, s85
	v_lshl_add_u64 v[220:221], s[86:87], 0, v[128:129]
	global_load_lds_dwordx4 v[218:219], off
	s_add_i32 m0, s85, 0x2000
	v_lshl_add_u64 v[222:223], s[62:63], 0, v[134:135]
	global_load_lds_dwordx4 v[220:221], off
	s_mov_b32 m0, s25
	v_lshl_add_u64 v[224:225], s[62:63], 0, v[130:131]
	global_load_lds_dwordx4 v[222:223], off
	s_mov_b32 m0, s26
	s_nop 0
	global_load_lds_dwordx4 v[224:225], off
	s_waitcnt vmcnt(24)
	s_waitcnt lgkmcnt(0)
	s_barrier
	s_setprio 1
	s_waitcnt lgkmcnt(0)
	v_mfma_f32_16x16x32_bf16 v[60:63], v[152:155], v[184:187], v[60:63]
	v_mfma_f32_16x16x32_bf16 v[56:59], v[160:163], v[184:187], v[56:59]
	v_mfma_f32_16x16x32_bf16 v[44:47], v[152:155], v[192:195], v[44:47]
	v_mfma_f32_16x16x32_bf16 v[40:43], v[160:163], v[192:195], v[40:43]
	v_mfma_f32_16x16x32_bf16 v[28:31], v[152:155], v[200:203], v[28:31]
	v_mfma_f32_16x16x32_bf16 v[24:27], v[160:163], v[200:203], v[24:27]
	v_mfma_f32_16x16x32_bf16 v[12:15], v[152:155], v[208:211], v[12:15]
	v_mfma_f32_16x16x32_bf16 v[8:11], v[160:163], v[208:211], v[8:11]
	v_mfma_f32_16x16x32_bf16 v[60:63], v[156:159], v[188:191], v[60:63]
	v_mfma_f32_16x16x32_bf16 v[56:59], v[164:167], v[188:191], v[56:59]
	v_mfma_f32_16x16x32_bf16 v[44:47], v[156:159], v[196:199], v[44:47]
	v_mfma_f32_16x16x32_bf16 v[40:43], v[164:167], v[196:199], v[40:43]
	v_mfma_f32_16x16x32_bf16 v[28:31], v[156:159], v[204:207], v[28:31]
	v_mfma_f32_16x16x32_bf16 v[24:27], v[164:167], v[204:207], v[24:27]
	v_mfma_f32_16x16x32_bf16 v[12:15], v[156:159], v[212:215], v[12:15]
	v_mfma_f32_16x16x32_bf16 v[8:11], v[164:167], v[212:215], v[8:11]
	s_setprio 0
	s_setprio 1
	v_mfma_f32_16x16x32_bf16 v[52:55], v[168:171], v[184:187], v[52:55]
	v_mfma_f32_16x16x32_bf16 v[48:51], v[176:179], v[184:187], v[48:51]
	v_mfma_f32_16x16x32_bf16 v[36:39], v[168:171], v[192:195], v[36:39]
	v_mfma_f32_16x16x32_bf16 v[32:35], v[176:179], v[192:195], v[32:35]
	v_mfma_f32_16x16x32_bf16 v[20:23], v[168:171], v[200:203], v[20:23]
	v_mfma_f32_16x16x32_bf16 v[16:19], v[176:179], v[200:203], v[16:19]
	v_mfma_f32_16x16x32_bf16 v[4:7], v[168:171], v[208:211], v[4:7]
	v_mfma_f32_16x16x32_bf16 v[0:3], v[176:179], v[208:211], v[0:3]
	v_mfma_f32_16x16x32_bf16 v[52:55], v[172:175], v[188:191], v[52:55]
	v_mfma_f32_16x16x32_bf16 v[48:51], v[180:183], v[188:191], v[48:51]
	v_mfma_f32_16x16x32_bf16 v[36:39], v[172:175], v[196:199], v[36:39]
	v_mfma_f32_16x16x32_bf16 v[32:35], v[180:183], v[196:199], v[32:35]
	v_mfma_f32_16x16x32_bf16 v[20:23], v[172:175], v[204:207], v[20:23]
	v_mfma_f32_16x16x32_bf16 v[16:19], v[180:183], v[204:207], v[16:19]
	v_mfma_f32_16x16x32_bf16 v[4:7], v[172:175], v[212:215], v[4:7]
	v_mfma_f32_16x16x32_bf16 v[0:3], v[180:183], v[212:215], v[0:3]
	s_setprio 0
	s_barrier
	s_add_i32 s85, 0, 0x18000
	s_add_i32 s86, 0, 0x1c000
	v_add_u32_e32 v164, s85, v147
	v_add_u32_e32 v180, s86, v147
	ds_read_b128 v[152:155], v164
	ds_read_b128 v[156:159], v164 offset:1024
	ds_read_b128 v[160:163], v164 offset:2048
	ds_read_b128 v[164:167], v164 offset:3072
	ds_read_b128 v[168:171], v180
	ds_read_b128 v[172:175], v180 offset:1024
	ds_read_b128 v[176:179], v180 offset:2048
	ds_read_b128 v[180:183], v180 offset:3072
	s_add_u32 s62, s62, s34
	s_addc_u32 s63, s63, s35
	s_mov_b32 m0, s27
	v_lshl_add_u64 v[226:227], s[62:63], 0, v[134:135]
	ds_read_b128 v[184:187], v151 offset:32768
	ds_read_b128 v[188:191], v151 offset:33792
	ds_read_b128 v[192:195], v151 offset:34816
	ds_read_b128 v[196:199], v151 offset:35840
	ds_read_b128 v[200:203], v151 offset:36864
	ds_read_b128 v[204:207], v151 offset:37888
	ds_read_b128 v[208:211], v151 offset:38912
	ds_read_b128 v[212:215], v151 offset:39936
	global_load_lds_dwordx4 v[226:227], off
	v_lshl_add_u64 v[226:227], s[62:63], 0, v[130:131]
	s_mov_b32 m0, s28
	s_nop 0
	global_load_lds_dwordx4 v[226:227], off
	s_waitcnt vmcnt(24)
	s_waitcnt lgkmcnt(0)
	s_barrier
	s_setprio 1
	s_waitcnt lgkmcnt(0)
	v_mfma_f32_16x16x32_bf16 v[120:123], v[152:155], v[184:187], v[120:123]
	v_mfma_f32_16x16x32_bf16 v[124:127], v[160:163], v[184:187], v[124:127]
	v_mfma_f32_16x16x32_bf16 v[108:111], v[152:155], v[192:195], v[108:111]
	v_mfma_f32_16x16x32_bf16 v[104:107], v[160:163], v[192:195], v[104:107]
	v_mfma_f32_16x16x32_bf16 v[92:95], v[152:155], v[200:203], v[92:95]
	v_mfma_f32_16x16x32_bf16 v[88:91], v[160:163], v[200:203], v[88:91]
	v_mfma_f32_16x16x32_bf16 v[76:79], v[152:155], v[208:211], v[76:79]
	v_mfma_f32_16x16x32_bf16 v[72:75], v[160:163], v[208:211], v[72:75]
	v_mfma_f32_16x16x32_bf16 v[120:123], v[156:159], v[188:191], v[120:123]
	v_mfma_f32_16x16x32_bf16 v[124:127], v[164:167], v[188:191], v[124:127]
	v_mfma_f32_16x16x32_bf16 v[108:111], v[156:159], v[196:199], v[108:111]
	v_mfma_f32_16x16x32_bf16 v[104:107], v[164:167], v[196:199], v[104:107]
	v_mfma_f32_16x16x32_bf16 v[92:95], v[156:159], v[204:207], v[92:95]
	v_mfma_f32_16x16x32_bf16 v[88:91], v[164:167], v[204:207], v[88:91]
	v_mfma_f32_16x16x32_bf16 v[76:79], v[156:159], v[212:215], v[76:79]
	v_mfma_f32_16x16x32_bf16 v[72:75], v[164:167], v[212:215], v[72:75]
	s_setprio 0
	s_setprio 1
	v_mfma_f32_16x16x32_bf16 v[116:119], v[168:171], v[184:187], v[116:119]
	v_mfma_f32_16x16x32_bf16 v[112:115], v[176:179], v[184:187], v[112:115]
	v_mfma_f32_16x16x32_bf16 v[100:103], v[168:171], v[192:195], v[100:103]
	v_mfma_f32_16x16x32_bf16 v[96:99], v[176:179], v[192:195], v[96:99]
	v_mfma_f32_16x16x32_bf16 v[84:87], v[168:171], v[200:203], v[84:87]
	v_mfma_f32_16x16x32_bf16 v[80:83], v[176:179], v[200:203], v[80:83]
	v_mfma_f32_16x16x32_bf16 v[68:71], v[168:171], v[208:211], v[68:71]
	v_mfma_f32_16x16x32_bf16 v[64:67], v[176:179], v[208:211], v[64:67]
	v_mfma_f32_16x16x32_bf16 v[116:119], v[172:175], v[188:191], v[116:119]
	v_mfma_f32_16x16x32_bf16 v[112:115], v[180:183], v[188:191], v[112:115]
	v_mfma_f32_16x16x32_bf16 v[100:103], v[172:175], v[196:199], v[100:103]
	v_mfma_f32_16x16x32_bf16 v[96:99], v[180:183], v[196:199], v[96:99]
	v_mfma_f32_16x16x32_bf16 v[84:87], v[172:175], v[204:207], v[84:87]
	v_mfma_f32_16x16x32_bf16 v[80:83], v[180:183], v[204:207], v[80:83]
	v_mfma_f32_16x16x32_bf16 v[68:71], v[172:175], v[212:215], v[68:71]
	v_mfma_f32_16x16x32_bf16 v[64:67], v[180:183], v[212:215], v[64:67]
	s_setprio 0
	s_barrier
	s_add_i32 s62, s85, s24
	v_lshl_add_u64 v[144:145], v[144:145], 0, s[44:45]
	s_mov_b32 m0, s62
	ds_read_b128 v[184:187], v151 offset:49152
	ds_read_b128 v[188:191], v151 offset:50176
	ds_read_b128 v[192:195], v151 offset:51200
	ds_read_b128 v[196:199], v151 offset:52224
	ds_read_b128 v[200:203], v151 offset:53248
	ds_read_b128 v[204:207], v151 offset:54272
	ds_read_b128 v[208:211], v151 offset:55296
	ds_read_b128 v[212:215], v151 offset:56320
	global_load_lds_dwordx4 v[144:145], off
	v_lshl_add_u64 v[144:145], v[216:217], 0, s[44:45]
	s_add_i32 m0, s62, 0x2000
	s_add_i32 s62, s86, s24
	global_load_lds_dwordx4 v[144:145], off
	v_lshl_add_u64 v[144:145], v[218:219], 0, s[44:45]
	s_mov_b32 m0, s62
	s_nop 0
	global_load_lds_dwordx4 v[144:145], off
	v_lshl_add_u64 v[144:145], v[220:221], 0, s[44:45]
	s_add_i32 m0, s62, 0x2000
	s_nop 0
	global_load_lds_dwordx4 v[144:145], off
	v_lshl_add_u64 v[144:145], v[222:223], 0, s[44:45]
	s_mov_b32 m0, s30
	s_nop 0
	global_load_lds_dwordx4 v[144:145], off
	v_lshl_add_u64 v[144:145], v[224:225], 0, s[44:45]
	s_mov_b32 m0, s31
	s_nop 0
	global_load_lds_dwordx4 v[144:145], off
	s_waitcnt vmcnt(8)
	s_waitcnt lgkmcnt(0)
	s_barrier
	s_setprio 1
	s_waitcnt lgkmcnt(0)
	v_mfma_f32_16x16x32_bf16 v[60:63], v[152:155], v[184:187], v[60:63]
	v_mfma_f32_16x16x32_bf16 v[56:59], v[160:163], v[184:187], v[56:59]
	v_mfma_f32_16x16x32_bf16 v[44:47], v[152:155], v[192:195], v[44:47]
	v_mfma_f32_16x16x32_bf16 v[40:43], v[160:163], v[192:195], v[40:43]
	v_mfma_f32_16x16x32_bf16 v[28:31], v[152:155], v[200:203], v[28:31]
	v_mfma_f32_16x16x32_bf16 v[24:27], v[160:163], v[200:203], v[24:27]
	v_mfma_f32_16x16x32_bf16 v[12:15], v[152:155], v[208:211], v[12:15]
	v_mfma_f32_16x16x32_bf16 v[8:11], v[160:163], v[208:211], v[8:11]
	v_mfma_f32_16x16x32_bf16 v[60:63], v[156:159], v[188:191], v[60:63]
	v_mfma_f32_16x16x32_bf16 v[56:59], v[164:167], v[188:191], v[56:59]
	v_mfma_f32_16x16x32_bf16 v[44:47], v[156:159], v[196:199], v[44:47]
	v_mfma_f32_16x16x32_bf16 v[40:43], v[164:167], v[196:199], v[40:43]
	v_mfma_f32_16x16x32_bf16 v[28:31], v[156:159], v[204:207], v[28:31]
	v_mfma_f32_16x16x32_bf16 v[24:27], v[164:167], v[204:207], v[24:27]
	v_mfma_f32_16x16x32_bf16 v[12:15], v[156:159], v[212:215], v[12:15]
	v_mfma_f32_16x16x32_bf16 v[8:11], v[164:167], v[212:215], v[8:11]
	s_setprio 0
	s_setprio 1
	v_mfma_f32_16x16x32_bf16 v[52:55], v[168:171], v[184:187], v[52:55]
	v_mfma_f32_16x16x32_bf16 v[48:51], v[176:179], v[184:187], v[48:51]
	v_mfma_f32_16x16x32_bf16 v[36:39], v[168:171], v[192:195], v[36:39]
	v_mfma_f32_16x16x32_bf16 v[32:35], v[176:179], v[192:195], v[32:35]
	v_mfma_f32_16x16x32_bf16 v[20:23], v[168:171], v[200:203], v[20:23]
	v_mfma_f32_16x16x32_bf16 v[16:19], v[176:179], v[200:203], v[16:19]
	v_mfma_f32_16x16x32_bf16 v[4:7], v[168:171], v[208:211], v[4:7]
	v_mfma_f32_16x16x32_bf16 v[0:3], v[176:179], v[208:211], v[0:3]
	v_mfma_f32_16x16x32_bf16 v[52:55], v[172:175], v[188:191], v[52:55]
	v_mfma_f32_16x16x32_bf16 v[48:51], v[180:183], v[188:191], v[48:51]
	v_mfma_f32_16x16x32_bf16 v[36:39], v[172:175], v[196:199], v[36:39]
	v_mfma_f32_16x16x32_bf16 v[32:35], v[180:183], v[196:199], v[32:35]
	v_mfma_f32_16x16x32_bf16 v[20:23], v[172:175], v[204:207], v[20:23]
	v_mfma_f32_16x16x32_bf16 v[16:19], v[180:183], v[204:207], v[16:19]
	v_mfma_f32_16x16x32_bf16 v[4:7], v[172:175], v[212:215], v[4:7]
	v_mfma_f32_16x16x32_bf16 v[0:3], v[180:183], v[212:215], v[0:3]
	s_setprio 0
	s_barrier
	s_add_u32 s60, s60, 0x100
	s_addc_u32 s61, s61, 0
	s_add_u32 s82, s82, 0x100
	s_addc_u32 s83, s83, 0
	s_cmp_ge_i32 s84, s64
	s_mov_b32 s62, s84
	s_cbranch_scc1 .LBB0_857

.LBB0_859:
	s_add_u32 s98, s10, 0x80
	s_addc_u32 s99, s11, 0
	v_lshl_add_u64 v[250:251], s[98:99], 0, v[136:137]
	s_add_i32 m0, s25, 0xc000
	s_nop 0
	global_load_lds_dwordx4 v[250:251], off
	v_lshl_add_u64 v[250:251], s[98:99], 0, v[138:139]
	s_add_i32 m0, s25, 0xe000
	s_nop 0
	global_load_lds_dwordx4 v[250:251], off
	v_lshl_add_u32 v152, s80, 8, v146
	v_lshl_or_b32 v144, s81, 8, v148
	v_ashrrev_i32_e32 v153, 31, v152
	v_max_f32_e32 v120, 0, v120
	v_ashrrev_i32_e32 v145, 31, v144
	v_lshlrev_b64 v[154:155], 13, v[152:153]
	v_max_f32_e32 v121, 0, v121
	v_max_f32_e32 v122, 0, v122
	v_max_f32_e32 v123, 0, v123
	v_lshl_add_u64 v[154:155], s[16:17], 0, v[154:155]
	v_lshlrev_b64 v[156:157], 1, v[144:145]
	v_max_f32_e32 v124, 0, v124
	v_mul_f32_e32 v120, v120, v120
	v_max_f32_e32 v125, 0, v125
	v_max_f32_e32 v126, 0, v126
	v_max_f32_e32 v127, 0, v127
	v_max_f32_e32 v112, 0, v112
	v_lshl_add_u64 v[144:145], v[154:155], 0, v[156:157]
	v_mul_f32_e32 v121, v121, v121
	v_mul_f32_e32 v122, v122, v122
	v_mul_f32_e32 v123, v123, v123
	v_cvt_pk_bf16_f32 v120, v120, v121
	v_max_f32_e32 v113, 0, v113
	v_max_f32_e32 v114, 0, v114
	v_mul_f32_e32 v124, v124, v124
	v_mul_f32_e32 v125, v125, v125
	v_mul_f32_e32 v126, v126, v126
	v_mul_f32_e32 v127, v127, v127
	v_cvt_pk_bf16_f32 v121, v122, v123
	v_cvt_pk_bf16_f32 v122, v124, v125
	v_cvt_pk_bf16_f32 v123, v126, v127
	global_store_dwordx4 v[144:145], v[120:123], off
	s_nop 1
	v_mul_f32_e32 v120, v112, v112
	v_max_f32_e32 v112, 0, v117
	v_max_f32_e32 v116, 0, v116
	v_mul_f32_e32 v117, v113, v113
	v_max_f32_e32 v113, 0, v118
	v_mul_f32_e32 v118, v114, v114
	v_max_f32_e32 v114, 0, v119
	v_max_f32_e32 v115, 0, v115
	v_mul_f32_e32 v112, v112, v112
	v_mul_f32_e32 v116, v116, v116
	v_mul_f32_e32 v113, v113, v113
	v_mul_f32_e32 v114, v114, v114
	v_mul_f32_e32 v115, v115, v115
	v_cvt_pk_bf16_f32 v112, v116, v112
	v_max_f32_e32 v104, 0, v104
	v_cvt_pk_bf16_f32 v113, v113, v114
	v_cvt_pk_bf16_f32 v114, v120, v117
	v_cvt_pk_bf16_f32 v115, v118, v115
	global_store_dwordx4 v[144:145], v[112:115], off offset:256
	s_nop 1
	v_max_f32_e32 v105, 0, v105
	v_or_b32_e32 v112, 16, v152
	v_max_f32_e32 v106, 0, v106
	v_ashrrev_i32_e32 v113, 31, v112
	v_mul_f32_e32 v114, v104, v104
	v_max_f32_e32 v104, 0, v109
	v_lshlrev_b64 v[112:113], 13, v[112:113]
	v_max_f32_e32 v108, 0, v108
	v_mul_f32_e32 v109, v105, v105
	v_max_f32_e32 v105, 0, v110
	v_mul_f32_e32 v110, v106, v106
	v_max_f32_e32 v106, 0, v111
	v_max_f32_e32 v107, 0, v107
	v_lshl_add_u64 v[112:113], s[16:17], 0, v[112:113]
	v_mul_f32_e32 v104, v104, v104
	v_max_f32_e32 v96, 0, v96
	v_lshl_add_u64 v[112:113], v[112:113], 0, v[156:157]
	v_mul_f32_e32 v108, v108, v108
	v_mul_f32_e32 v105, v105, v105
	v_mul_f32_e32 v106, v106, v106
	v_mul_f32_e32 v107, v107, v107
	v_cvt_pk_bf16_f32 v104, v108, v104
	v_max_f32_e32 v97, 0, v97
	v_max_f32_e32 v98, 0, v98
	v_cvt_pk_bf16_f32 v105, v105, v106
	v_cvt_pk_bf16_f32 v106, v114, v109
	v_cvt_pk_bf16_f32 v107, v110, v107
	global_store_dwordx4 v[112:113], v[104:107], off
	s_nop 1
	v_mul_f32_e32 v104, v96, v96
	v_max_f32_e32 v96, 0, v101
	v_max_f32_e32 v100, 0, v100
	v_mul_f32_e32 v101, v97, v97
	v_max_f32_e32 v97, 0, v102
	v_mul_f32_e32 v102, v98, v98
	v_max_f32_e32 v98, 0, v103
	v_max_f32_e32 v99, 0, v99
	v_mul_f32_e32 v96, v96, v96
	v_mul_f32_e32 v100, v100, v100
	v_mul_f32_e32 v97, v97, v97
	v_mul_f32_e32 v98, v98, v98
	v_mul_f32_e32 v99, v99, v99
	v_cvt_pk_bf16_f32 v96, v100, v96
	v_max_f32_e32 v88, 0, v88
	v_cvt_pk_bf16_f32 v97, v97, v98
	v_cvt_pk_bf16_f32 v98, v104, v101
	v_cvt_pk_bf16_f32 v99, v102, v99
	global_store_dwordx4 v[112:113], v[96:99], off offset:256
	s_nop 1
	v_max_f32_e32 v89, 0, v89
	v_or_b32_e32 v96, 32, v152
	v_max_f32_e32 v90, 0, v90
	v_ashrrev_i32_e32 v97, 31, v96
	v_mul_f32_e32 v98, v88, v88
	v_max_f32_e32 v88, 0, v93
	v_lshlrev_b64 v[96:97], 13, v[96:97]
	v_max_f32_e32 v92, 0, v92
	v_mul_f32_e32 v93, v89, v89
	v_max_f32_e32 v89, 0, v94
	v_mul_f32_e32 v94, v90, v90
	v_max_f32_e32 v90, 0, v95
	v_max_f32_e32 v91, 0, v91
	v_lshl_add_u64 v[96:97], s[16:17], 0, v[96:97]
	v_mul_f32_e32 v88, v88, v88
	v_max_f32_e32 v80, 0, v80
	v_lshl_add_u64 v[96:97], v[96:97], 0, v[156:157]
	v_mul_f32_e32 v92, v92, v92
	v_mul_f32_e32 v89, v89, v89
	v_mul_f32_e32 v90, v90, v90
	v_mul_f32_e32 v91, v91, v91
	v_cvt_pk_bf16_f32 v88, v92, v88
	v_max_f32_e32 v81, 0, v81
	v_max_f32_e32 v82, 0, v82
	v_cvt_pk_bf16_f32 v89, v89, v90
	v_cvt_pk_bf16_f32 v90, v98, v93
	v_cvt_pk_bf16_f32 v91, v94, v91
	global_store_dwordx4 v[96:97], v[88:91], off
	s_nop 1
	v_mul_f32_e32 v88, v80, v80
	v_max_f32_e32 v80, 0, v85
	v_max_f32_e32 v84, 0, v84
	v_mul_f32_e32 v85, v81, v81
	v_max_f32_e32 v81, 0, v86
	v_mul_f32_e32 v86, v82, v82
	v_max_f32_e32 v82, 0, v87
	v_max_f32_e32 v83, 0, v83
	v_mul_f32_e32 v80, v80, v80
	v_mul_f32_e32 v84, v84, v84
	v_mul_f32_e32 v81, v81, v81
	v_mul_f32_e32 v82, v82, v82
	v_mul_f32_e32 v83, v83, v83
	v_cvt_pk_bf16_f32 v80, v84, v80
	v_max_f32_e32 v72, 0, v72
	v_cvt_pk_bf16_f32 v81, v81, v82
	v_cvt_pk_bf16_f32 v82, v88, v85
	v_cvt_pk_bf16_f32 v83, v86, v83
	global_store_dwordx4 v[96:97], v[80:83], off offset:256
	s_nop 1
	v_max_f32_e32 v73, 0, v73
	v_or_b32_e32 v80, 48, v152
	v_max_f32_e32 v74, 0, v74
	v_ashrrev_i32_e32 v81, 31, v80
	v_mul_f32_e32 v82, v72, v72
	v_max_f32_e32 v72, 0, v77
	v_lshlrev_b64 v[80:81], 13, v[80:81]
	v_max_f32_e32 v76, 0, v76
	v_mul_f32_e32 v77, v73, v73
	v_max_f32_e32 v73, 0, v78
	v_mul_f32_e32 v78, v74, v74
	v_max_f32_e32 v74, 0, v79
	v_max_f32_e32 v75, 0, v75
	v_lshl_add_u64 v[80:81], s[16:17], 0, v[80:81]
	v_mul_f32_e32 v72, v72, v72
	v_max_f32_e32 v64, 0, v64
	v_max_f32_e32 v65, 0, v65
	v_max_f32_e32 v66, 0, v66
	v_lshl_add_u64 v[80:81], v[80:81], 0, v[156:157]
	v_mul_f32_e32 v76, v76, v76
	v_mul_f32_e32 v73, v73, v73
	v_mul_f32_e32 v74, v74, v74
	v_mul_f32_e32 v75, v75, v75
	v_cvt_pk_bf16_f32 v72, v76, v72
	v_cvt_pk_bf16_f32 v73, v73, v74
	v_cvt_pk_bf16_f32 v74, v82, v77
	v_cvt_pk_bf16_f32 v75, v78, v75
	global_store_dwordx4 v[80:81], v[72:75], off
	v_max_f32_e32 v68, 0, v68
	v_max_f32_e32 v67, 0, v67
	v_mul_f32_e32 v72, v64, v64
	v_max_f32_e32 v64, 0, v69
	v_mul_f32_e32 v69, v65, v65
	v_max_f32_e32 v65, 0, v70
	v_mul_f32_e32 v70, v66, v66
	v_max_f32_e32 v66, 0, v71
	v_mul_f32_e32 v64, v64, v64
	v_mul_f32_e32 v65, v65, v65
	v_mul_f32_e32 v66, v66, v66
	v_max_f32_e32 v56, 0, v56
	v_mul_f32_e32 v68, v68, v68
	v_mul_f32_e32 v67, v67, v67
	v_cvt_pk_bf16_f32 v64, v68, v64
	v_cvt_pk_bf16_f32 v65, v65, v66
	v_cvt_pk_bf16_f32 v66, v72, v69
	v_max_f32_e32 v57, 0, v57
	v_max_f32_e32 v58, 0, v58
	v_cvt_pk_bf16_f32 v67, v70, v67
	global_store_dwordx4 v[80:81], v[64:67], off offset:256
	s_nop 1
	v_max_f32_e32 v60, 0, v60
	v_mul_f32_e32 v66, v56, v56
	v_max_f32_e32 v56, 0, v61
	v_mul_f32_e32 v61, v57, v57
	v_max_f32_e32 v57, 0, v62
	v_mul_f32_e32 v62, v58, v58
	v_max_f32_e32 v58, 0, v63
	v_mul_f32_e32 v60, v60, v60
	v_mul_f32_e32 v56, v56, v56
	v_max_f32_e32 v59, 0, v59
	v_mul_f32_e32 v57, v57, v57
	v_mul_f32_e32 v58, v58, v58
	v_cvt_pk_bf16_f32 v56, v60, v56
	v_add_co_u32_e32 v60, vcc, s69, v144
	v_max_f32_e32 v48, 0, v48
	v_max_f32_e32 v49, 0, v49
	v_max_f32_e32 v50, 0, v50
	v_mul_f32_e32 v59, v59, v59
	v_cvt_pk_bf16_f32 v57, v57, v58
	v_cvt_pk_bf16_f32 v58, v66, v61
	v_addc_co_u32_e32 v61, vcc, 0, v145, vcc
	v_cvt_pk_bf16_f32 v59, v62, v59
	global_store_dwordx4 v[60:61], v[56:59], off
	v_max_f32_e32 v52, 0, v52
	v_max_f32_e32 v51, 0, v51
	v_mul_f32_e32 v56, v48, v48
	v_max_f32_e32 v48, 0, v53
	v_mul_f32_e32 v53, v49, v49
	v_max_f32_e32 v49, 0, v54
	v_mul_f32_e32 v54, v50, v50
	v_max_f32_e32 v50, 0, v55
	v_mul_f32_e32 v48, v48, v48
	v_mul_f32_e32 v49, v49, v49
	v_mul_f32_e32 v50, v50, v50
	v_max_f32_e32 v40, 0, v40
	v_lshl_add_u64 v[64:65], v[144:145], 0, s[50:51]
	v_mul_f32_e32 v52, v52, v52
	v_mul_f32_e32 v51, v51, v51
	v_cvt_pk_bf16_f32 v48, v52, v48
	v_cvt_pk_bf16_f32 v49, v49, v50
	v_cvt_pk_bf16_f32 v50, v56, v53
	v_max_f32_e32 v41, 0, v41
	v_max_f32_e32 v42, 0, v42
	v_cvt_pk_bf16_f32 v51, v54, v51
	global_store_dwordx4 v[64:65], v[48:51], off offset:256
	s_nop 1
	v_max_f32_e32 v44, 0, v44
	v_mul_f32_e32 v50, v40, v40
	v_max_f32_e32 v40, 0, v45
	v_mul_f32_e32 v45, v41, v41
	v_max_f32_e32 v41, 0, v46
	v_mul_f32_e32 v46, v42, v42
	v_max_f32_e32 v42, 0, v47
	v_mul_f32_e32 v44, v44, v44
	v_mul_f32_e32 v40, v40, v40
	v_max_f32_e32 v43, 0, v43
	v_mul_f32_e32 v41, v41, v41
	v_mul_f32_e32 v42, v42, v42
	v_cvt_pk_bf16_f32 v40, v44, v40
	v_add_co_u32_e32 v44, vcc, s71, v144
	v_max_f32_e32 v32, 0, v32
	v_max_f32_e32 v33, 0, v33
	v_max_f32_e32 v34, 0, v34
	v_mul_f32_e32 v43, v43, v43
	v_cvt_pk_bf16_f32 v41, v41, v42
	v_cvt_pk_bf16_f32 v42, v50, v45
	v_addc_co_u32_e32 v45, vcc, 0, v145, vcc
	v_cvt_pk_bf16_f32 v43, v46, v43
	global_store_dwordx4 v[44:45], v[40:43], off
	v_max_f32_e32 v36, 0, v36
	v_max_f32_e32 v35, 0, v35
	v_mul_f32_e32 v40, v32, v32
	v_max_f32_e32 v32, 0, v37
	v_mul_f32_e32 v37, v33, v33
	v_max_f32_e32 v33, 0, v38
	v_mul_f32_e32 v38, v34, v34
	v_max_f32_e32 v34, 0, v39
	v_mul_f32_e32 v32, v32, v32
	v_mul_f32_e32 v33, v33, v33
	v_mul_f32_e32 v34, v34, v34
	v_max_f32_e32 v24, 0, v24
	v_lshl_add_u64 v[48:49], v[144:145], 0, s[52:53]
	v_mul_f32_e32 v36, v36, v36
	v_mul_f32_e32 v35, v35, v35
	v_cvt_pk_bf16_f32 v32, v36, v32
	v_cvt_pk_bf16_f32 v33, v33, v34
	v_cvt_pk_bf16_f32 v34, v40, v37
	v_max_f32_e32 v25, 0, v25
	v_max_f32_e32 v26, 0, v26
	v_cvt_pk_bf16_f32 v35, v38, v35
	global_store_dwordx4 v[48:49], v[32:35], off offset:256
	s_nop 1
	v_max_f32_e32 v28, 0, v28
	v_mul_f32_e32 v34, v24, v24
	v_max_f32_e32 v24, 0, v29
	v_mul_f32_e32 v29, v25, v25
	v_max_f32_e32 v25, 0, v30
	v_mul_f32_e32 v30, v26, v26
	v_max_f32_e32 v26, 0, v31
	v_mul_f32_e32 v28, v28, v28
	v_mul_f32_e32 v24, v24, v24
	v_max_f32_e32 v27, 0, v27
	v_mul_f32_e32 v25, v25, v25
	v_mul_f32_e32 v26, v26, v26
	v_cvt_pk_bf16_f32 v24, v28, v24
	v_add_co_u32_e32 v28, vcc, s72, v144
	v_max_f32_e32 v16, 0, v16
	v_max_f32_e32 v17, 0, v17
	v_max_f32_e32 v18, 0, v18
	v_mul_f32_e32 v27, v27, v27
	v_cvt_pk_bf16_f32 v25, v25, v26
	v_cvt_pk_bf16_f32 v26, v34, v29
	v_addc_co_u32_e32 v29, vcc, 0, v145, vcc
	v_cvt_pk_bf16_f32 v27, v30, v27
	global_store_dwordx4 v[28:29], v[24:27], off
	v_max_f32_e32 v20, 0, v20
	v_max_f32_e32 v19, 0, v19
	v_mul_f32_e32 v24, v16, v16
	v_max_f32_e32 v16, 0, v21
	v_mul_f32_e32 v21, v17, v17
	v_max_f32_e32 v17, 0, v22
	v_mul_f32_e32 v22, v18, v18
	v_max_f32_e32 v18, 0, v23
	v_mul_f32_e32 v16, v16, v16
	v_mul_f32_e32 v17, v17, v17
	v_mul_f32_e32 v18, v18, v18
	v_max_f32_e32 v8, 0, v8
	v_lshl_add_u64 v[32:33], v[144:145], 0, s[54:55]
	v_mul_f32_e32 v20, v20, v20
	v_mul_f32_e32 v19, v19, v19
	v_cvt_pk_bf16_f32 v16, v20, v16
	v_cvt_pk_bf16_f32 v17, v17, v18
	v_cvt_pk_bf16_f32 v18, v24, v21
	v_max_f32_e32 v9, 0, v9
	v_max_f32_e32 v10, 0, v10
	v_cvt_pk_bf16_f32 v19, v22, v19
	global_store_dwordx4 v[32:33], v[16:19], off offset:256
	s_nop 1
	v_max_f32_e32 v12, 0, v12
	v_mul_f32_e32 v18, v8, v8
	v_max_f32_e32 v8, 0, v13
	v_mul_f32_e32 v13, v9, v9
	v_max_f32_e32 v9, 0, v14
	v_mul_f32_e32 v14, v10, v10
	v_max_f32_e32 v10, 0, v15
	v_mul_f32_e32 v12, v12, v12
	v_mul_f32_e32 v8, v8, v8
	v_max_f32_e32 v11, 0, v11
	v_mul_f32_e32 v9, v9, v9
	v_mul_f32_e32 v10, v10, v10
	v_cvt_pk_bf16_f32 v8, v12, v8
	v_add_co_u32_e32 v12, vcc, s75, v144
	v_max_f32_e32 v0, 0, v0
	v_max_f32_e32 v1, 0, v1
	v_max_f32_e32 v2, 0, v2
	v_mul_f32_e32 v11, v11, v11
	v_cvt_pk_bf16_f32 v9, v9, v10
	v_cvt_pk_bf16_f32 v10, v18, v13
	v_addc_co_u32_e32 v13, vcc, 0, v145, vcc
	v_cvt_pk_bf16_f32 v11, v14, v11
	global_store_dwordx4 v[12:13], v[8:11], off
	v_max_f32_e32 v3, 0, v3
	v_max_f32_e32 v4, 0, v4
	v_mul_f32_e32 v8, v0, v0
	v_max_f32_e32 v0, 0, v5
	v_mul_f32_e32 v5, v1, v1
	v_max_f32_e32 v1, 0, v6
	v_mul_f32_e32 v6, v2, v2
	v_max_f32_e32 v2, 0, v7
	v_lshl_add_u64 v[16:17], v[144:145], 0, s[56:57]
	v_mul_f32_e32 v0, v0, v0
	v_mul_f32_e32 v1, v1, v1
	v_mul_f32_e32 v2, v2, v2
	v_mul_f32_e32 v3, v3, v3
	s_and_b64 vcc, exec, s[8:9]
	s_mov_b64 s[8:9], -1
	v_mul_f32_e32 v4, v4, v4
	v_cvt_pk_bf16_f32 v0, v4, v0
	v_cvt_pk_bf16_f32 v1, v1, v2
	v_cvt_pk_bf16_f32 v2, v8, v5
	v_cvt_pk_bf16_f32 v3, v6, v3
	global_store_dwordx4 v[16:17], v[0:3], off offset:256
	s_cbranch_vccnz .LBB0_843
	s_andn2_b64 vcc, exec, s[42:43]
	s_cbranch_vccnz .LBB0_842
	s_barrier
	s_branch .LBB0_842

	.amdhsa_kernel _Z6mk_fwdILi0ELi12EEv4Args
		.amdhsa_group_segment_fixed_size 0
		.amdhsa_private_segment_fixed_size 0
		.amdhsa_kernarg_size 504
		.amdhsa_user_sgpr_count 2
		.amdhsa_user_sgpr_dispatch_ptr 0
		.amdhsa_user_sgpr_queue_ptr 0
		.amdhsa_user_sgpr_kernarg_segment_ptr 1
		.amdhsa_user_sgpr_dispatch_id 0
		.amdhsa_user_sgpr_kernarg_preload_length 0
		.amdhsa_user_sgpr_kernarg_preload_offset 0
		.amdhsa_user_sgpr_private_segment_size 0
		.amdhsa_uses_dynamic_stack 0
		.amdhsa_enable_private_segment 0
		.amdhsa_system_sgpr_workgroup_id_x 1
		.amdhsa_system_sgpr_workgroup_id_y 0
		.amdhsa_system_sgpr_workgroup_id_z 0
		.amdhsa_system_sgpr_workgroup_info 0
		.amdhsa_system_vgpr_workitem_id 0
		.amdhsa_next_free_vgpr 252
		.amdhsa_next_free_sgpr 100
		.amdhsa_accum_offset 252
		.amdhsa_reserve_vcc 1
		.amdhsa_float_round_mode_32 0
		.amdhsa_float_round_mode_16_64 0
		.amdhsa_float_denorm_mode_32 3
		.amdhsa_float_denorm_mode_16_64 3
		.amdhsa_dx10_clamp 1
		.amdhsa_ieee_mode 1
		.amdhsa_fp16_overflow 0
		.amdhsa_tg_split 0
		.amdhsa_exception_fp_ieee_invalid_op 0
		.amdhsa_exception_fp_denorm_src 0
		.amdhsa_exception_fp_ieee_div_zero 0
		.amdhsa_exception_fp_ieee_overflow 0
		.amdhsa_exception_fp_ieee_underflow 0
		.amdhsa_exception_fp_ieee_inexact 0
		.amdhsa_exception_int_div_zero 0
	.end_amdhsa_kernel

amdhsa.kernels:
  - .agpr_count:     0
    .args:
      - .offset:         0
        .size:           248
        .value_kind:     by_value
      - .offset:         248
        .size:           4
        .value_kind:     hidden_block_count_x
      - .offset:         252
        .size:           4
        .value_kind:     hidden_block_count_y
      - .offset:         256
        .size:           4
        .value_kind:     hidden_block_count_z
      - .offset:         260
        .size:           2
        .value_kind:     hidden_group_size_x
      - .offset:         262
        .size:           2
        .value_kind:     hidden_group_size_y
      - .offset:         264
        .size:           2
        .value_kind:     hidden_group_size_z
      - .offset:         266
        .size:           2
        .value_kind:     hidden_remainder_x
      - .offset:         268
        .size:           2
        .value_kind:     hidden_remainder_y
      - .offset:         270
        .size:           2
        .value_kind:     hidden_remainder_z
      - .offset:         288
        .size:           8
        .value_kind:     hidden_global_offset_x
      - .offset:         296
        .size:           8
        .value_kind:     hidden_global_offset_y
      - .offset:         304
        .size:           8
        .value_kind:     hidden_global_offset_z
      - .offset:         312
        .size:           2
        .value_kind:     hidden_grid_dims
      - .offset:         368
        .size:           4
        .value_kind:     hidden_dynamic_lds_size
    .group_segment_fixed_size: 0
    .kernarg_segment_align: 8
    .kernarg_segment_size: 504
    .language:       OpenCL C
    .language_version:
      - 2
      - 0
    .max_flat_workgroup_size: 512
    .name:           _Z6mk_fwdILi0ELi12EEv4Args
    .private_segment_fixed_size: 0
    .sgpr_count:     106
    .sgpr_spill_count: 16
    .symbol:         _Z6mk_fwdILi0ELi12EEv4Args.kd
    .uniform_work_group_size: 1
    .uses_dynamic_stack: false
    .vgpr_count:     252
    .vgpr_spill_count: 0
    .wavefront_size: 64
